# v18 + nt (streaming) policy on the scan phase state stores only
# speedup vs baseline: 1.0131x; 1.0131x over previous
; #define RS_DMA(c, slot) do { const int cc_ = ((c) < 63) ? (c) : 63; _Pragma("unroll") for (int i = 0; i < 4; ++i) \
;             __builtin_amdgcn_global_load_lds((const unsigned*)(src[i] + cc_ * 128), (LAS unsigned*)(lds + (slot) * 32768 + dst[i]), 16, 0, 0); } while (0)
; __device__ __forceinline__ void ret_scan_phase(LAS unsigned char* lds, const bf16* KVT, bf16* ST, int G, int bid) {
;     ...
;     for (int u = bid; u < 256; u += G) {
;         const int h = u & 7, dq = (u >> 6) & 3, es = (u >> 3) & 7;
;         const float gam = 1.0f - exp2f(-5.0f - (float)h); const float dec = exp2f(128.0f * log2f(gam));
;         const bf16* src[4]; unsigned dst[4];
; #pragma unroll
;         for (int i = 0; i < 4; ++i) { const int bI = 4 * w + i, row = 4 * (bI & 15) + (lane >> 4), piece = (lane & 15) ^ (row & 15);
;             const size_t grow = (bI < 16) ? (size_t)(h * 256 + dq * 64 + row) : (size_t)(2048 + h * 512 + es * 64 + row);
;             src[i] = KVT + grow * KVT_LD + piece * 8; dst[i] = (unsigned)((bI < 16 ? 0 : 16384) + (bI & 15) * 1024); }
;     ...
;         const int e0l = 16 * (w & 3), d0l = 32 * (w >> 2);
;         const int offA0 = (d0l + li) * 256, offA1 = (d0l + 16 + li) * 256, offB = 16384 + (e0l + li) * 256;
;         const int stw = (e0l + li) * 144 + (d0l + 4 * g) * 2;
;         const int str_ = (tid >> 3) * 144 + (tid & 7) * 16;
;         bf16* stp = ST + ((size_t)(h * 64 * 512 + es * 64 + (tid >> 3))) * 256 + dq * 64 + (tid & 7) * 8;
;         f32x4 acc[2]; acc[0] = (f32x4){0.f, 0.f, 0.f, 0.f}; acc[1] = acc[0];
;         RS_DMA(0, 0); RS_DMA(1, 1); RS_DMA(2, 2);
;     ...
;         RS_STEP(0, 8); RS_STEP(1, 8); RS_STEP(2, 9);
.LBB0_179:
	s_and_b32 s20, s7, 7
	s_lshl_b32 s20, s20, 15
	s_and_b32 s23, s6, 0x1c0
	s_or_b32 s20, s23, s20
	v_add_u32_e32 v8, s20, v49
	v_ashrrev_i32_e32 v9, 31, v8
	s_lshl_b32 s20, s22, 1
	v_lshlrev_b64 v[8:9], 9, v[8:9]
	s_and_b32 s20, s20, 0x180
	v_or_b32_e32 v8, s20, v8
	s_and_b32 s20, s22, 7
	v_cvt_f32_ubyte0_e32 v0, s20
	v_sub_f32_e32 v0, 0xc0a00000, v0
	s_mov_b32 s43, 0xc2fc0000
	v_cmp_gt_f32_e32 vcc, s43, v0
	v_lshl_add_u64 v[28:29], v[24:25], 0, v[8:9]
	s_and_b32 s23, s22, 0xc0
	v_cndmask_b32_e32 v8, 0, v221, vcc
	v_add_f32_e32 v0, v0, v8
	v_exp_f32_e32 v0, v0
	s_and_b64 s[38:39], vcc, exec
	s_cselect_b32 s37, 0xffffffc0, 0
	v_mov_b32_e32 v8, 0x42000000
	v_ldexp_f32 v0, v0, s37
	v_sub_f32_e32 v0, 1.0, v0
	s_mov_b32 s37, 0x800000
	v_cmp_gt_f32_e32 vcc, s37, v0
	s_and_b64 s[38:39], vcc, exec
	s_cselect_b32 s37, 32, 0
	s_lshl_b32 s38, s22, 3
	v_ldexp_f32 v0, v0, s37
	s_lshl_b32 s37, s20, 9
	s_and_b32 s40, s38, 0x1c0
	v_log_f32_e32 v0, v0
	s_or_b32 s37, s37, s40
	s_lshl_b32 s38, s20, 8
	s_addk_i32 s37, 0x800
	s_or_b32 s41, s38, s23
	s_and_b64 s[38:39], s[0:1], exec
	v_cndmask_b32_e32 v8, 0, v8, vcc
	s_cselect_b32 s38, s41, s37
	v_sub_f32_e32 v10, v0, v8
	v_or_b32_e32 v0, s38, v65
	s_and_b64 s[38:39], s[2:3], exec
	v_mul_u32_u24_e32 v0, 0x4080, v0
	s_cselect_b32 s38, s41, s37
	v_lshl_add_u64 v[30:31], v[16:17], 0, v[0:1]
	v_or_b32_e32 v0, s38, v54
	s_and_b64 s[38:39], s[4:5], exec
	v_mul_u32_u24_e32 v0, 0x4080, v0
	s_cselect_b32 s38, s41, s37
	v_lshl_add_u64 v[32:33], v[18:19], 0, v[0:1]
	v_or_b32_e32 v0, s38, v55
	s_and_b64 s[38:39], s[10:11], exec
	v_mul_u32_u24_e32 v0, 0x4080, v0
	s_cselect_b32 s37, s41, s37
	s_lshl_b32 s20, s20, 15
	v_mul_f32_e32 v11, 0x43000000, v10
	v_lshl_add_u64 v[34:35], v[20:21], 0, v[0:1]
	v_or_b32_e32 v0, s37, v56
	s_or_b32 s20, s40, s20
	v_mul_u32_u24_e32 v0, 0x4080, v0
	v_add_u32_e32 v8, s20, v49
	v_cmp_gt_f32_e32 vcc, s43, v11
	v_lshl_add_u64 v[36:37], v[22:23], 0, v[0:1]
	v_ashrrev_i32_e32 v9, 31, v8
	v_readlane_b32 s38, v253, 24
	v_cndmask_b32_e32 v0, 0, v221, vcc
	v_lshlrev_b64 v[8:9], 9, v[8:9]
	v_readlane_b32 s39, v253, 25
	s_add_i32 s42, s12, 0
	v_fmac_f32_e32 v0, 0x43000000, v10
	v_lshl_add_u64 v[8:9], s[38:39], 0, v[8:9]
	s_mov_b32 m0, s42
	s_add_i32 s39, s13, 0
	v_exp_f32_e32 v0, v0
	s_lshl_b32 s20, s23, 1
	global_load_lds_dwordx4 v[30:31], off
	s_mov_b32 m0, s39
	s_add_i32 s40, s16, 0
	s_add_i32 s41, s17, 0
	global_load_lds_dwordx4 v[32:33], off
	s_mov_b32 m0, s40
	s_and_b64 s[44:45], vcc, exec
	v_lshl_add_u64 v[8:9], v[8:9], 0, s[20:21]
	global_load_lds_dwordx4 v[34:35], off
	s_mov_b32 m0, s41
	s_cselect_b32 s20, 0xffffffc0, 0
	s_mov_b64 s[44:45], 0x100
	s_add_i32 s38, s42, 0x8000
	global_load_lds_dwordx4 v[36:37], off
	v_ldexp_f32 v38, v0, s20
	v_lshl_add_u64 v[10:11], v[30:31], 0, s[44:45]
	s_mov_b32 m0, s38
	s_add_i32 s20, s39, 0x8000
	global_load_lds_dwordx4 v[10:11], off
	v_lshl_add_u64 v[10:11], v[32:33], 0, s[44:45]
	s_mov_b32 m0, s20
	s_add_i32 s23, s40, 0x8000
	global_load_lds_dwordx4 v[10:11], off
	v_lshl_add_u64 v[10:11], v[34:35], 0, s[44:45]
	s_mov_b32 m0, s23
	s_add_i32 s37, s41, 0x8000
	global_load_lds_dwordx4 v[10:11], off
	v_lshl_add_u64 v[10:11], v[36:37], 0, s[44:45]
	s_mov_b32 m0, s37
	s_mov_b64 s[44:45], 0x200
	global_load_lds_dwordx4 v[10:11], off
	v_lshl_add_u64 v[10:11], v[30:31], 0, s[44:45]
	s_add_i32 m0, s19, s12
	v_add_u32_e32 v0, v3, v57
	global_load_lds_dwordx4 v[10:11], off
	v_lshl_add_u64 v[10:11], v[32:33], 0, s[44:45]
	s_add_i32 m0, s19, s13
	v_add_u32_e32 v39, v50, v57
	global_load_lds_dwordx4 v[10:11], off
	v_lshl_add_u64 v[10:11], v[34:35], 0, s[44:45]
	s_add_i32 m0, s19, s16
	v_add_u32_e32 v106, v3, v58
	global_load_lds_dwordx4 v[10:11], off
	v_lshl_add_u64 v[10:11], v[36:37], 0, s[44:45]
	s_add_i32 m0, s19, s17
	v_add_u32_e32 v107, v50, v58
	global_load_lds_dwordx4 v[10:11], off
	s_waitcnt vmcnt(8)
	s_barrier
	v_add_u32_e32 v108, v3, v59
	v_add_u32_e32 v109, v50, v59
	v_add_u32_e32 v110, v3, v60
	v_add_u32_e32 v114, v50, v60
	ds_read_b128 v[10:13], v0 offset:16384
	ds_read_b128 v[40:43], v39
	ds_read_b128 v[66:69], v39 offset:4096
	ds_read_b128 v[70:73], v106 offset:16384
	ds_read_b128 v[74:77], v107
	ds_read_b128 v[78:81], v107 offset:4096
	ds_read_b128 v[82:85], v108 offset:16384
	ds_read_b128 v[86:89], v109
	ds_read_b128 v[90:93], v109 offset:4096
	ds_read_b128 v[94:97], v110 offset:16384
	ds_read_b128 v[98:101], v114
	ds_read_b128 v[102:105], v114 offset:4096
	s_waitcnt lgkmcnt(0)
	v_mfma_f32_16x16x32_bf16 v[40:43], v[40:43], v[10:13], 0
	v_mfma_f32_16x16x32_bf16 v[10:13], v[66:69], v[10:13], 0
	v_mfma_f32_16x16x32_bf16 v[10:13], v[78:81], v[70:73], v[10:13]
	v_mfma_f32_16x16x32_bf16 v[40:43], v[74:77], v[70:73], v[40:43]
	v_mfma_f32_16x16x32_bf16 v[10:13], v[90:93], v[82:85], v[10:13]
	v_mfma_f32_16x16x32_bf16 v[40:43], v[86:89], v[82:85], v[40:43]
	v_mfma_f32_16x16x32_bf16 v[10:13], v[102:105], v[94:97], v[10:13]
	v_mfma_f32_16x16x32_bf16 v[66:69], v[98:101], v[94:97], v[40:43]
	s_nop 7
	v_pk_mul_f32 v[68:69], v[38:39], v[68:69] op_sel_hi:[0,1]
	v_pk_mul_f32 v[66:67], v[38:39], v[66:67] op_sel_hi:[0,1]
	v_cvt_pk_bf16_f32 v14, v66, v67
	v_cvt_pk_bf16_f32 v15, v68, v69
	ds_write_b64 v51, v[14:15]
	v_pk_mul_f32 v[12:13], v[38:39], v[12:13] op_sel_hi:[0,1]
	v_pk_mul_f32 v[10:11], v[38:39], v[10:11] op_sel_hi:[0,1]
	v_cvt_pk_bf16_f32 v14, v10, v11
	v_cvt_pk_bf16_f32 v15, v12, v13
	ds_write_b64 v51, v[14:15] offset:32
	s_mov_b64 s[44:45], 0x300
	s_waitcnt lgkmcnt(0)
	v_lshl_add_u64 v[14:15], v[30:31], 0, s[44:45]
	s_add_i32 m0, s91, s12
	v_mov_b32_e32 v27, v1
	global_load_lds_dwordx4 v[14:15], off
	v_lshl_add_u64 v[14:15], v[32:33], 0, s[44:45]
	s_add_i32 m0, s91, s13
	v_lshl_add_u64 v[42:43], v[8:9], 0, v[26:27]
	global_load_lds_dwordx4 v[14:15], off
	v_lshl_add_u64 v[14:15], v[34:35], 0, s[44:45]
	s_add_i32 m0, s91, s16
	s_mov_b32 s43, 0x40000
	global_load_lds_dwordx4 v[14:15], off
	v_lshl_add_u64 v[14:15], v[36:37], 0, s[44:45]
	s_add_i32 m0, s91, s17
	v_add_co_u32_e32 v8, vcc, s43, v42
	global_load_lds_dwordx4 v[14:15], off
	s_waitcnt vmcnt(8)
	s_barrier
; __device__ __forceinline__ void ret_scan_phase(LAS unsigned char* lds, const bf16* KVT, bf16* ST, int G, int bid) {
;     ...
;         RS_STEP(0, 8); RS_STEP(1, 8); RS_STEP(2, 9);
	ds_read_b128 v[70:73], v52
	v_addc_co_u32_e32 v9, vcc, 0, v43, vcc
	v_mov_b32_e32 v40, v38
	v_mov_b32_e32 v41, v38
	s_waitcnt lgkmcnt(0)
	global_store_dwordx4 v[8:9], v[70:73], off nt
	ds_read_b128 v[70:73], v0 offset:49152
	ds_read_b128 v[74:77], v39 offset:32768
	ds_read_b128 v[78:81], v39 offset:36864
	ds_read_b128 v[82:85], v106 offset:49152
	ds_read_b128 v[86:89], v107 offset:32768
	ds_read_b128 v[90:93], v107 offset:36864
	ds_read_b128 v[94:97], v108 offset:49152
	ds_read_b128 v[98:101], v109 offset:32768
	ds_read_b128 v[102:105], v109 offset:36864
	ds_read_b128 v[106:109], v110 offset:49152
	ds_read_b128 v[110:113], v114 offset:32768
	ds_read_b128 v[114:117], v114 offset:36864
	s_waitcnt lgkmcnt(0)
	v_mfma_f32_16x16x32_bf16 v[66:69], v[74:77], v[70:73], v[66:69]
	v_mfma_f32_16x16x32_bf16 v[8:11], v[78:81], v[70:73], v[10:13]
	v_mfma_f32_16x16x32_bf16 v[12:15], v[86:89], v[82:85], v[66:69]
	v_mfma_f32_16x16x32_bf16 v[8:11], v[90:93], v[82:85], v[8:11]
	v_mfma_f32_16x16x32_bf16 v[12:15], v[98:101], v[94:97], v[12:15]
	v_mfma_f32_16x16x32_bf16 v[8:11], v[102:105], v[94:97], v[8:11]
	v_mfma_f32_16x16x32_bf16 v[12:15], v[110:113], v[106:109], v[12:15]
	v_mfma_f32_16x16x32_bf16 v[8:11], v[114:117], v[106:109], v[8:11]
	v_readlane_b32 s43, v252, 21
	s_nop 5
	v_pk_mul_f32 v[14:15], v[38:39], v[14:15] op_sel_hi:[0,1]
	v_pk_mul_f32 v[12:13], v[38:39], v[12:13] op_sel_hi:[0,1]
	v_cvt_pk_bf16_f32 v66, v12, v13
	v_cvt_pk_bf16_f32 v67, v14, v15
	v_add_u32_e32 v0, s43, v48
	ds_write_b64 v0, v[66:67]
	v_pk_mul_f32 v[10:11], v[38:39], v[10:11] op_sel_hi:[0,1]
	v_pk_mul_f32 v[8:9], v[38:39], v[8:9] op_sel_hi:[0,1]
	v_cvt_pk_bf16_f32 v66, v8, v9
	v_cvt_pk_bf16_f32 v67, v10, v11
	ds_write_b64 v0, v[66:67] offset:32
	s_mov_b64 s[44:45], 0x400
	s_waitcnt lgkmcnt(0)
	v_lshl_add_u64 v[66:67], v[30:31], 0, s[44:45]
	s_mov_b32 m0, s42
	v_add_u32_e32 v0, s43, v2
	global_load_lds_dwordx4 v[66:67], off
	v_lshl_add_u64 v[66:67], v[32:33], 0, s[44:45]
	s_mov_b32 m0, s39
	s_mov_b32 s39, 0x80000
	global_load_lds_dwordx4 v[66:67], off
	v_lshl_add_u64 v[66:67], v[34:35], 0, s[44:45]
	s_mov_b32 m0, s40
	v_add_co_u32_e32 v70, vcc, s39, v42
	global_load_lds_dwordx4 v[66:67], off
	v_lshl_add_u64 v[66:67], v[36:37], 0, s[44:45]
	s_mov_b32 m0, s41
	v_addc_co_u32_e32 v71, vcc, 0, v43, vcc
	global_load_lds_dwordx4 v[66:67], off
	s_waitcnt vmcnt(9)
	s_barrier
	ds_read_b128 v[66:69], v0
	v_add_u32_e32 v0, v61, v47
	s_waitcnt lgkmcnt(0)
	global_store_dwordx4 v[70:71], v[66:69], off nt
	ds_read_b128 v[66:69], v0
	v_add_u32_e32 v0, v53, v57
	ds_read_b128 v[70:73], v0
	v_add_u32_e32 v0, v61, v45
	ds_read_b128 v[74:77], v0
	v_add_u32_e32 v0, v62, v47
	ds_read_b128 v[78:81], v0
	v_add_u32_e32 v0, v53, v58
	ds_read_b128 v[82:85], v0
	v_add_u32_e32 v0, v62, v45
	ds_read_b128 v[86:89], v0
	v_add_u32_e32 v0, v63, v47
	ds_read_b128 v[90:93], v0
	v_add_u32_e32 v0, v53, v59
	ds_read_b128 v[94:97], v0
	v_add_u32_e32 v0, v63, v45
	ds_read_b128 v[98:101], v0
	v_add_u32_e32 v0, v64, v47
	ds_read_b128 v[102:105], v0
	v_add_u32_e32 v0, v53, v60
	ds_read_b128 v[106:109], v0
	v_add_u32_e32 v0, v64, v45
	ds_read_b128 v[110:113], v0
	s_waitcnt lgkmcnt(0)
	v_mfma_f32_16x16x32_bf16 v[12:15], v[70:73], v[66:69], v[12:15]
	v_mfma_f32_16x16x32_bf16 v[8:11], v[74:77], v[66:69], v[8:11]
	v_mfma_f32_16x16x32_bf16 v[12:15], v[82:85], v[78:81], v[12:15]
	v_mfma_f32_16x16x32_bf16 v[8:11], v[86:89], v[78:81], v[8:11]
	v_mfma_f32_16x16x32_bf16 v[12:15], v[94:97], v[90:93], v[12:15]
	v_mfma_f32_16x16x32_bf16 v[8:11], v[98:101], v[90:93], v[8:11]
	v_mfma_f32_16x16x32_bf16 v[12:15], v[106:109], v[102:105], v[12:15]
	v_mfma_f32_16x16x32_bf16 v[66:69], v[110:113], v[102:105], v[8:11]
	s_nop 6
	v_mul_f32_e64 v10, v38, v14
	v_mul_f32_e64 v11, v38, v15
	v_pk_mul_f32 v[8:9], v[38:39], v[12:13] op_sel_hi:[0,1]
	v_cvt_pk_bf16_f32 v12, v8, v9
	v_cvt_pk_bf16_f32 v13, v10, v11
	s_mov_b32 m0, s38
	ds_write_b64 v51, v[12:13]
	v_pk_mul_f32 v[14:15], v[38:39], v[68:69] op_sel_hi:[0,1]
	v_pk_mul_f32 v[12:13], v[38:39], v[66:67] op_sel_hi:[0,1]
	v_cvt_pk_bf16_f32 v66, v12, v13
	v_cvt_pk_bf16_f32 v67, v14, v15
	ds_write_b64 v51, v[66:67] offset:32
	s_mov_b64 s[38:39], 0x500
	s_waitcnt lgkmcnt(0)
	v_lshl_add_u64 v[66:67], v[30:31], 0, s[38:39]
	global_load_lds_dwordx4 v[66:67], off
	v_lshl_add_u64 v[66:67], v[32:33], 0, s[38:39]
	s_mov_b32 m0, s20
	s_nop 0
	global_load_lds_dwordx4 v[66:67], off
	v_lshl_add_u64 v[66:67], v[34:35], 0, s[38:39]
	s_mov_b32 m0, s23
	s_mov_b32 s23, 6
	global_load_lds_dwordx4 v[66:67], off
	v_lshl_add_u64 v[66:67], v[36:37], 0, s[38:39]
	s_mov_b32 m0, s37
	s_mov_b32 s37, 0x30000
	global_load_lds_dwordx4 v[66:67], off
; #define LAS __attribute__((address_space(3)))
; __device__ __forceinline__ void ret_scan_phase(LAS unsigned char* lds, const bf16* KVT, bf16* ST, int G, int bid) {
;     ...
;         RS_STEP(0, 8); RS_STEP(1, 8); RS_STEP(2, 9);
; #pragma unroll 1
;         for (int c = 3; c < 63; ++c) RS_STEP(c, 10);
;         asm volatile("s_waitcnt vmcnt(0)\n\ts_barrier" ::: "memory");
;         { const v4u x_ = *(const LAS v4u*)(lds + 131072 + (62 & 1) * 9216 + str_); *(v4u*)(stp + (size_t)63 * (512 * 256)) = x_; }
.LBB0_180:
	s_add_i32 s20, s23, -3
	s_andn2_b32 s38, 1, s20
	s_mulk_i32 s38, 0x2400
	s_waitcnt vmcnt(10)
	s_barrier
	v_add_u32_e32 v0, s38, v52
	ds_read_b128 v[66:69], v0
	s_add_i32 s38, s37, 0xfffe8000
	s_and_b32 s38, s38, 0x18000
	s_add_i32 s38, s38, 0
	v_add_u32_e32 v0, s38, v46
	v_add_u32_e32 v27, s38, v44
	v_add_u32_e32 v39, v0, v57
	s_waitcnt lgkmcnt(0)
	global_store_dwordx4 v[28:29], v[66:69], off nt
	ds_read_b128 v[66:69], v39 offset:16384
	v_add_u32_e32 v39, v27, v57
	ds_read_b128 v[70:73], v39
	ds_read_b128 v[74:77], v39 offset:4096
	v_add_u32_e32 v39, v0, v58
	ds_read_b128 v[78:81], v39 offset:16384
	v_add_u32_e32 v39, v27, v58
	ds_read_b128 v[82:85], v39
	ds_read_b128 v[86:89], v39 offset:4096
	v_add_u32_e32 v39, v0, v59
	ds_read_b128 v[90:93], v39 offset:16384
	v_add_u32_e32 v39, v27, v59
	v_add_u32_e32 v0, v0, v60
	ds_read_b128 v[94:97], v39
	ds_read_b128 v[98:101], v39 offset:4096
	ds_read_b128 v[102:105], v0 offset:16384
	v_add_u32_e32 v0, v27, v60
	ds_read_b128 v[106:109], v0
	ds_read_b128 v[110:113], v0 offset:4096
	s_waitcnt lgkmcnt(0)
	v_mfma_f32_16x16x32_bf16 v[8:11], v[70:73], v[66:69], v[8:11]
	v_mfma_f32_16x16x32_bf16 v[12:15], v[74:77], v[66:69], v[12:15]
	v_mfma_f32_16x16x32_bf16 v[8:11], v[82:85], v[78:81], v[8:11]
	v_mfma_f32_16x16x32_bf16 v[12:15], v[86:89], v[78:81], v[12:15]
	v_mfma_f32_16x16x32_bf16 v[8:11], v[94:97], v[90:93], v[8:11]
	v_mfma_f32_16x16x32_bf16 v[12:15], v[98:101], v[90:93], v[12:15]
	v_mfma_f32_16x16x32_bf16 v[8:11], v[106:109], v[102:105], v[8:11]
	v_mfma_f32_16x16x32_bf16 v[12:15], v[110:113], v[102:105], v[12:15]
	s_bitcmp1_b32 s20, 0
	s_cselect_b32 s20, 0x2400, 0
	v_mov_b32_e32 v39, v38
	v_add_u32_e32 v0, s20, v51
	s_nop 2
	v_pk_mul_f32 v[10:11], v[38:39], v[10:11]
	v_pk_mul_f32 v[8:9], v[40:41], v[8:9]
	s_min_u32 s20, s23, 63
	v_cvt_pk_bf16_f32 v66, v8, v9
	v_cvt_pk_bf16_f32 v67, v10, v11
	s_and_b32 s38, s37, 0x18000
	ds_write_b64 v0, v[66:67]
	v_pk_mul_f32 v[14:15], v[38:39], v[14:15]
	v_pk_mul_f32 v[12:13], v[40:41], v[12:13]
	s_add_i32 s38, s38, 0
	v_cvt_pk_bf16_f32 v66, v12, v13
	v_cvt_pk_bf16_f32 v67, v14, v15
	ds_write_b64 v0, v[66:67] offset:32
	s_lshl_b32 s20, s20, 8
	s_waitcnt lgkmcnt(0)
	v_lshl_add_u64 v[66:67], v[30:31], 0, s[20:21]
	s_add_i32 m0, s38, s12
	s_add_i32 s23, s23, 1
	global_load_lds_dwordx4 v[66:67], off
	v_lshl_add_u64 v[66:67], v[32:33], 0, s[20:21]
	s_add_i32 m0, s38, s13
	s_add_i32 s37, s37, 0x8000
	global_load_lds_dwordx4 v[66:67], off
	v_lshl_add_u64 v[66:67], v[34:35], 0, s[20:21]
	s_add_i32 m0, s38, s16
	s_nop 0
	global_load_lds_dwordx4 v[66:67], off
	v_lshl_add_u64 v[66:67], v[36:37], 0, s[20:21]
	s_add_i32 m0, s38, s17
	s_mov_b64 s[38:39], 0x40000
	global_load_lds_dwordx4 v[66:67], off
	v_lshl_add_u64 v[28:29], v[28:29], 0, s[38:39]
	s_cmpk_eq_i32 s23, 0x42
	s_cbranch_scc0 .LBB0_180
	s_waitcnt vmcnt(0)
	s_barrier
	ds_read_b128 v[8:11], v52
	v_add_co_u32_e32 v12, vcc, 0xfc0000, v42
	s_add_i32 s22, s22, s90
	s_nop 0
	v_addc_co_u32_e32 v13, vcc, 0, v43, vcc
	s_waitcnt lgkmcnt(0)
	global_store_dwordx4 v[12:13], v[8:11], off nt
	s_waitcnt lgkmcnt(0)
	s_barrier
	s_add_i32 s7, s7, s90
	s_add_i32 s6, s6, s8
	s_cmpk_gt_i32 s22, 0xff
	s_cbranch_scc0 .LBB0_179
	s_movk_i32 s37, 0x2000
